# closed-form next-unit index also in the P1 in-projection and P6 out-projection unit headers
# speedup vs baseline: 1.0009x; 1.0009x over previous
;     __host__ __device__ bool next(int i, Unit& u) const { const int L = i * G + c; if (L >= n) return false; u.pm = L; u.pn = L >> 2; return true; }
;     __host__ __device__ bool next(int i, Unit& u) const {
;         const long L = (long)i * G + c; if (L >= nwg) return false;
;         int wgid = (int)L; { const int q = nwg / NXCD, r = nwg % NXCD, xcd = wgid % NXCD, off = wgid / NXCD; wgid = (xcd < r ? xcd * (q + 1) : r * (q + 1) + (xcd - r) * q) + off; }
;         const int nig = WGM * nN, gid = wgid / nig, fm = gid * WGM, gsz = (nM - fm) < WGM ? (nM - fm) : WGM;
;         u.pm = fm + ((wgid % nig) % gsz); u.pn = (wgid % nig) / gsz; return true;
;     }
; template <class Epi, class Sched, bool ALIGN_EPI>
; __device__ __forceinline__ void gemm_phase(PG8_LAS unsigned char* lds, const Gemm g, const Sched& S, const Epi& E) {
;     ...
;         const bool has_next = S.next(ui + 1, nxt);
;         const size_t tail_ = has_next ? 0 : tailoff; const char* nA = (has_next ? (const char*)g.A + (size_t)nxt.pm * tstepA : cA) + (has_next ? 0 : tailoffA); const char* nB = (has_next ? (const char*)g.Bt + (size_t)nxt.pn * tstepB : cB) + tail_;
.LBB0_400:
	s_add_i32 s38, s38, 1
	s_mul_i32 s0, s38, s44
	s_mul_hi_u32 s1, s38, s33
	s_add_i32 s1, s1, s0
	s_mul_i32 s0, s38, s33
	s_add_u32 s18, s0, s2
	s_addc_u32 s19, s1, s30
	v_cmp_gt_i64_e32 vcc, s[18:19], v[146:147]
	v_cmp_lt_i64_e64 s[0:1], s[18:19], v[144:145]
	s_mov_b64 s[20:21], 0xf00
	s_cbranch_vccnz .LBB0_402
	s_add_i32 s14, s4, 4
	s_mov_b32 s16, s22
	s_mov_b64 s[20:21], 0

;     __host__ __device__ bool next(int i, Unit& u) const { const int L = i * G + c; if (L >= n) return false; u.pm = L; u.pn = L >> 2; return true; }
;     __host__ __device__ bool next(int i, Unit& u) const {
;         const long L = (long)i * G + c; if (L >= nwg) return false;
;         int wgid = (int)L; { const int q = nwg / NXCD, r = nwg % NXCD, xcd = wgid % NXCD, off = wgid / NXCD; wgid = (xcd < r ? xcd * (q + 1) : r * (q + 1) + (xcd - r) * q) + off; }
;         const int nig = WGM * nN, gid = wgid / nig, fm = gid * WGM, gsz = (nM - fm) < WGM ? (nM - fm) : WGM;
;         u.pm = fm + ((wgid % nig) % gsz); u.pn = (wgid % nig) / gsz; return true;
;     }
; template <class Epi, class Sched, bool ALIGN_EPI>
; __device__ __forceinline__ void gemm_phase(PG8_LAS unsigned char* lds, const Gemm g, const Sched& S, const Epi& E) {
;     ...
;         const bool has_next = S.next(ui + 1, nxt);
;         const size_t tail_ = has_next ? 0 : tailoff; const char* nA = (has_next ? (const char*)g.A + (size_t)nxt.pm * tstepA : cA) + (has_next ? 0 : tailoffA); const char* nB = (has_next ? (const char*)g.Bt + (size_t)nxt.pn * tstepB : cB) + tail_;
.LBB0_832:
	s_add_i32 s51, s51, 1
	s_mul_i32 s0, s51, s54
	s_mul_hi_u32 s1, s51, s33
	s_add_i32 s1, s1, s0
	s_mul_i32 s0, s51, s33
	s_add_u32 s30, s0, s74
	s_addc_u32 s31, s1, s3
	v_cmp_gt_i64_e32 vcc, s[30:31], v[148:149]
	v_cmp_lt_i64_e64 s[0:1], s[30:31], v[146:147]
	s_mov_b64 s[34:35], 0xf00
	s_cbranch_vccnz .LBB0_838
	s_add_i32 s26, s61, 4
	s_mov_b32 s28, s36
	s_mov_b64 s[34:35], 0
